# P0 transposes re-deal: blocks 0..127 (two adaLN items) take chunk bid (+ cheap third-round chunk for bid<60); blocks 128..255 take chunks bid, bid+128, bid+256
# baseline (speedup 1.0000x reference)
.LBB0_28:
	s_lshl_b32 s98, s92, 3
	s_mov_b32 s99, 0x7fffffff
	s_cmpk_eq_u32 s92, 0x100
	s_cbranch_scc0 .Ltr4_pre
	s_movk_i32 s98, 0x1000
	s_cmpk_gt_u32 s96, 0x7f
	s_cbranch_scc0 .Ltr4_pre
	s_movk_i32 s98, 0x400
	s_movk_i32 s99, 0xc00

.LBB0_31:
	s_or_b64 exec, exec, s[16:17]
	v_cvt_f32_u32_e32 v7, v12
	v_sub_u32_e32 v17, 0, v12
	v_sub_u32_e32 v16, 0, v5
	v_max_i32_e32 v16, v5, v16
	v_rcp_iflag_f32_e32 v7, v7
	v_ashrrev_i32_e32 v13, 31, v5
	v_mul_f32_e32 v7, 0x4f7ffffe, v7
	v_cvt_u32_f32_e32 v7, v7
	v_mul_lo_u32 v17, v17, v7
	v_mul_hi_u32 v17, v7, v17
	v_add_u32_e32 v7, v7, v17
	v_mul_hi_u32 v7, v16, v7
	v_mul_lo_u32 v17, v7, v12
	v_sub_u32_e32 v16, v16, v17
	v_add_u32_e32 v40, 1, v7
	v_cmp_ge_u32_e64 s[0:1], v16, v12
	v_sub_u32_e32 v17, v16, v12
	s_nop 0
	v_cndmask_b32_e64 v7, v7, v40, s[0:1]
	v_cndmask_b32_e64 v16, v16, v17, s[0:1]
	v_add_u32_e32 v17, 1, v7
	v_cmp_ge_u32_e64 s[0:1], v16, v12
	s_nop 1
	v_cndmask_b32_e64 v7, v7, v17, s[0:1]
	v_xor_b32_e32 v7, v7, v13
	v_sub_u32_e32 v7, v7, v13
	v_mul_lo_u32 v12, v7, v12
	v_sub_u32_e32 v5, v5, v12
	v_lshlrev_b32_e32 v16, 6, v7
	v_lshlrev_b32_e32 v12, 6, v5
	v_or_b32_e32 v7, v16, v21
	v_ashrrev_i32_e32 v13, 31, v12
	v_ashrrev_i32_e32 v17, 31, v16
	v_or_b32_e32 v40, 4, v7
	v_or_b32_e32 v44, 8, v7
	v_lshl_add_u64 v[18:19], v[12:13], 2, v[18:19]
	v_mul_lo_u32 v13, v14, v17
	v_mul_lo_u32 v42, v15, v40
	v_mad_u64_u32 v[40:41], s[0:1], v14, v40, 0
	v_mul_lo_u32 v46, v15, v44
	v_mad_u64_u32 v[44:45], s[0:1], v14, v44, 0
	v_lshl_add_u64 v[18:19], v[18:19], 0, v[2:3]
	v_add3_u32 v41, v41, v13, v42
	v_add3_u32 v45, v45, v13, v46
	v_or_b32_e32 v46, 12, v7
	v_lshl_add_u64 v[40:41], v[40:41], 2, v[18:19]
	v_mul_lo_u32 v48, v15, v46
	v_mad_u64_u32 v[46:47], s[0:1], v14, v46, 0
	v_or_b32_e32 v52, 16, v7
	global_load_dwordx4 v[40:43], v[40:41], off
	v_add3_u32 v47, v47, v13, v48
	v_mul_lo_u32 v54, v15, v52
	v_mad_u64_u32 v[52:53], s[0:1], v14, v52, 0
	v_lshl_add_u64 v[44:45], v[44:45], 2, v[18:19]
	v_lshl_add_u64 v[48:49], v[46:47], 2, v[18:19]
	v_add3_u32 v53, v53, v13, v54
	v_or_b32_e32 v54, 20, v7
	global_load_dwordx4 v[44:47], v[44:45], off
	s_nop 0
	global_load_dwordx4 v[48:51], v[48:49], off
	v_mul_lo_u32 v56, v15, v54
	v_mad_u64_u32 v[54:55], s[0:1], v14, v54, 0
	v_add3_u32 v55, v55, v13, v56
	v_or_b32_e32 v60, 24, v7
	v_lshl_add_u64 v[52:53], v[52:53], 2, v[18:19]
	v_lshl_add_u64 v[56:57], v[54:55], 2, v[18:19]
	v_mul_lo_u32 v62, v15, v60
	v_mad_u64_u32 v[60:61], s[0:1], v14, v60, 0
	global_load_dwordx4 v[52:55], v[52:53], off
	s_nop 0
	global_load_dwordx4 v[56:59], v[56:57], off
	v_add3_u32 v61, v61, v13, v62
	v_or_b32_e32 v62, 28, v7
	v_mul_lo_u32 v64, v15, v62
	v_mad_u64_u32 v[62:63], s[0:1], v14, v62, 0
	v_add3_u32 v63, v63, v13, v64
	v_lshl_add_u64 v[60:61], v[60:61], 2, v[18:19]
	v_lshl_add_u64 v[64:65], v[62:63], 2, v[18:19]
	v_or_b32_e32 v72, 32, v7
	global_load_dwordx4 v[60:63], v[60:61], off
	s_nop 0
	global_load_dwordx4 v[64:67], v[64:65], off
	v_mul_lo_u32 v70, v15, v7
	v_mad_u64_u32 v[68:69], s[0:1], v14, v7, 0
	v_or_b32_e32 v74, 36, v7
	v_mul_lo_u32 v75, v15, v72
	v_mad_u64_u32 v[72:73], s[0:1], v14, v72, 0
	v_add3_u32 v69, v69, v13, v70
	v_mul_lo_u32 v76, v15, v74
	v_add3_u32 v73, v73, v13, v75
	v_mad_u64_u32 v[74:75], s[0:1], v14, v74, 0
	v_lshl_add_u64 v[68:69], v[68:69], 2, v[18:19]
	v_add3_u32 v75, v75, v13, v76
	v_or_b32_e32 v80, 40, v7
	global_load_dwordx4 v[68:71], v[68:69], off
	v_lshl_add_u64 v[72:73], v[72:73], 2, v[18:19]
	v_lshl_add_u64 v[76:77], v[74:75], 2, v[18:19]
	v_mul_lo_u32 v82, v15, v80
	v_mad_u64_u32 v[80:81], s[0:1], v14, v80, 0
	global_load_dwordx4 v[72:75], v[72:73], off
	s_nop 0
	global_load_dwordx4 v[76:79], v[76:77], off
	v_add3_u32 v81, v81, v13, v82
	v_or_b32_e32 v82, 44, v7
	v_mul_lo_u32 v84, v15, v82
	v_mad_u64_u32 v[82:83], s[0:1], v14, v82, 0
	v_add3_u32 v83, v83, v13, v84
	v_lshl_add_u64 v[80:81], v[80:81], 2, v[18:19]
	v_lshl_add_u64 v[84:85], v[82:83], 2, v[18:19]
	v_or_b32_e32 v88, 48, v7
	global_load_dwordx4 v[80:83], v[80:81], off
	s_nop 0
	global_load_dwordx4 v[84:87], v[84:85], off
	v_mul_lo_u32 v90, v15, v88
	v_mad_u64_u32 v[88:89], s[0:1], v14, v88, 0
	v_add3_u32 v89, v89, v13, v90
	v_or_b32_e32 v92, 52, v7
	v_lshl_add_u64 v[88:89], v[88:89], 2, v[18:19]
	v_mul_lo_u32 v94, v15, v92
	v_mad_u64_u32 v[92:93], s[0:1], v14, v92, 0
	global_load_dwordx4 v[88:91], v[88:89], off
	v_add3_u32 v93, v93, v13, v94
	v_or_b32_e32 v94, 56, v7
	v_lshl_add_u64 v[92:93], v[92:93], 2, v[18:19]
	v_mul_lo_u32 v95, v15, v94
	v_mad_u64_u32 v[96:97], s[0:1], v14, v94, 0
	v_add3_u32 v97, v97, v13, v95
	v_or_b32_e32 v7, 60, v7
	global_load_dwordx4 v[92:95], v[92:93], off
	v_mul_lo_u32 v100, v15, v7
	v_lshl_add_u64 v[96:97], v[96:97], 2, v[18:19]
	v_mad_u64_u32 v[14:15], s[0:1], v14, v7, 0
	global_load_dwordx4 v[96:99], v[96:97], off
	v_add3_u32 v15, v15, v13, v100
	v_lshl_add_u64 v[14:15], v[14:15], 2, v[18:19]
	global_load_dwordx4 v[100:103], v[14:15], off
	v_add_u32_e32 v7, 0x410, v39
	s_waitcnt vmcnt(15)
	ds_write2_b32 v7, v40, v41 offset1:1
	v_add_u32_e32 v7, 0x418, v39
	ds_write2_b32 v7, v42, v43 offset1:1
	v_add_u32_e32 v7, 0x820, v39
	v_cmp_eq_u32_e64 s[0:1], 64, v5
	v_add_u32_e32 v5, 0x828, v39
	s_waitcnt vmcnt(14)
	ds_write2_b32 v7, v44, v45 offset1:1
	v_add_u32_e32 v7, 0xc30, v39
	ds_write2_b32 v5, v46, v47 offset1:1
	s_waitcnt vmcnt(13)
	ds_write2_b32 v7, v48, v49 offset1:1
	v_add_u32_e32 v5, 0xc38, v39
	ds_write2_b32 v5, v50, v51 offset1:1
	v_add_u32_e32 v5, 0x1040, v39
	s_waitcnt vmcnt(12)
	ds_write2_b32 v5, v52, v53 offset1:1
	v_add_u32_e32 v5, 0x1048, v39
	ds_write2_b32 v5, v54, v55 offset1:1
	v_add_u32_e32 v5, 0x1450, v39
	s_waitcnt vmcnt(11)
	ds_write2_b32 v5, v56, v57 offset1:1
	v_add_u32_e32 v5, 0x1458, v39
	ds_write2_b32 v5, v58, v59 offset1:1
	v_add_u32_e32 v5, 0x1860, v39
	s_waitcnt vmcnt(10)
	ds_write2_b32 v5, v60, v61 offset1:1
	v_add_u32_e32 v5, 0x1868, v39
	ds_write2_b32 v5, v62, v63 offset1:1
	v_add_u32_e32 v5, 0x1c70, v39
	s_waitcnt vmcnt(9)
	ds_write2_b32 v5, v64, v65 offset1:1
	v_add_u32_e32 v5, 0x1c78, v39
	ds_write2_b32 v5, v66, v67 offset1:1
	v_add_u32_e32 v5, 0x2080, v39
	s_waitcnt vmcnt(8)
	ds_write2_b32 v39, v68, v69 offset1:1
	ds_write2_b32 v39, v70, v71 offset0:2 offset1:3
	s_and_b64 s[0:1], vcc, s[0:1]
	s_or_b64 vcc, s[12:13], s[0:1]
	v_cndmask_b32_e32 v7, v22, v24, vcc
	v_lshl_add_u32 v7, v7, 2, v23
	s_waitcnt vmcnt(7)
	ds_write2_b32 v5, v72, v73 offset1:1
	v_add_u32_e32 v5, 0x2088, v39
	ds_write2_b32 v5, v74, v75 offset1:1
	v_add_u32_e32 v5, 0x2490, v39
	s_waitcnt vmcnt(6)
	ds_write2_b32 v5, v76, v77 offset1:1
	v_add_u32_e32 v5, 0x2498, v39
	ds_write2_b32 v5, v78, v79 offset1:1
	v_add_u32_e32 v5, 0x28a0, v39
	v_lshl_add_u64 v[8:9], v[16:17], 1, v[8:9]
	s_waitcnt vmcnt(5)
	ds_write2_b32 v5, v80, v81 offset1:1
	v_add_u32_e32 v5, 0x28a8, v39
	ds_write2_b32 v5, v82, v83 offset1:1
	v_add_u32_e32 v5, 0x2cb0, v39
	s_waitcnt vmcnt(4)
	ds_write2_b32 v5, v84, v85 offset1:1
	v_add_u32_e32 v5, 0x2cb8, v39
	ds_write2_b32 v5, v86, v87 offset1:1
	v_add_u32_e32 v5, 0x30c0, v39
	s_waitcnt vmcnt(3)
	ds_write2_b32 v5, v88, v89 offset1:1
	v_add_u32_e32 v5, 0x30c8, v39
	ds_write2_b32 v5, v90, v91 offset1:1
	v_add_u32_e32 v5, 0x34d0, v39
	s_waitcnt vmcnt(2)
	ds_write2_b32 v5, v92, v93 offset1:1
	v_add_u32_e32 v5, 0x34d8, v39
	ds_write2_b32 v5, v94, v95 offset1:1
	v_add_u32_e32 v5, 0x38e0, v39
	s_waitcnt vmcnt(1)
	ds_write2_b32 v5, v96, v97 offset1:1
	v_add_u32_e32 v5, 0x38e8, v39
	ds_write2_b32 v5, v98, v99 offset1:1
	v_add_u32_e32 v5, 0x3cf0, v39
	s_waitcnt vmcnt(0)
	ds_write2_b32 v5, v100, v101 offset1:1
	v_add_u32_e32 v5, 0x3cf8, v39
	ds_write2_b32 v5, v102, v103 offset1:1
	s_waitcnt lgkmcnt(0)
	ds_read2_b32 v[14:15], v7 offset1:65
	ds_read2_b32 v[16:17], v7 offset0:130 offset1:195
	v_add_u32_e32 v7, 0x400, v7
	ds_read2_b32 v[18:19], v7 offset0:4 offset1:69
	ds_read2_b32 v[40:41], v7 offset0:134 offset1:199
	v_mov_b32_e32 v5, v3
	v_lshl_add_u64 v[8:9], v[8:9], 0, v[4:5]
	v_or_b32_e32 v5, v12, v22
	s_waitcnt lgkmcnt(3)
	v_cvt_pk_bf16_f32 v14, v14, v15
	s_waitcnt lgkmcnt(2)
	v_cvt_pk_bf16_f32 v15, v16, v17
	s_waitcnt lgkmcnt(1)
	v_cvt_pk_bf16_f32 v16, v18, v19
	v_mad_i64_i32 v[18:19], s[0:1], v6, v5, 0
	v_cndmask_b32_e32 v5, v25, v26, vcc
	v_lshl_add_u32 v5, v5, 2, v23
	s_waitcnt lgkmcnt(0)
	v_cvt_pk_bf16_f32 v17, v40, v41
	ds_read2_b32 v[40:41], v5 offset1:65
	ds_read2_b32 v[42:43], v5 offset0:130 offset1:195
	v_add_u32_e32 v5, 0x400, v5
	ds_read2_b32 v[44:45], v5 offset0:4 offset1:69
	ds_read2_b32 v[46:47], v5 offset0:134 offset1:199
	v_lshl_add_u64 v[18:19], v[18:19], 1, v[8:9]
	v_or_b32_e32 v5, v12, v25
	global_store_dwordx4 v[18:19], v[14:17], off
	v_mad_i64_i32 v[18:19], s[0:1], v6, v5, 0
	v_cndmask_b32_e32 v5, v27, v28, vcc
	v_lshl_add_u32 v5, v5, 2, v23
	s_waitcnt lgkmcnt(3)
	v_cvt_pk_bf16_f32 v14, v40, v41
	s_waitcnt lgkmcnt(2)
	v_cvt_pk_bf16_f32 v15, v42, v43
	ds_read2_b32 v[40:41], v5 offset1:65
	ds_read2_b32 v[42:43], v5 offset0:130 offset1:195
	v_add_u32_e32 v5, 0x400, v5
	s_waitcnt lgkmcnt(3)
	v_cvt_pk_bf16_f32 v16, v44, v45
	s_waitcnt lgkmcnt(2)
	v_cvt_pk_bf16_f32 v17, v46, v47
	ds_read2_b32 v[44:45], v5 offset0:4 offset1:69
	ds_read2_b32 v[46:47], v5 offset0:134 offset1:199
	v_lshl_add_u64 v[18:19], v[18:19], 1, v[8:9]
	v_or_b32_e32 v5, v12, v27
	global_store_dwordx4 v[18:19], v[14:17], off
	v_mad_i64_i32 v[18:19], s[0:1], v6, v5, 0
	v_cndmask_b32_e32 v5, v29, v30, vcc
	v_lshl_add_u32 v5, v5, 2, v23
	s_waitcnt lgkmcnt(3)
	v_cvt_pk_bf16_f32 v14, v40, v41
	s_waitcnt lgkmcnt(2)
	v_cvt_pk_bf16_f32 v15, v42, v43
	ds_read2_b32 v[40:41], v5 offset1:65
	ds_read2_b32 v[42:43], v5 offset0:130 offset1:195
	v_add_u32_e32 v5, 0x400, v5
	s_waitcnt lgkmcnt(3)
	v_cvt_pk_bf16_f32 v16, v44, v45
	s_waitcnt lgkmcnt(2)
	v_cvt_pk_bf16_f32 v17, v46, v47
	ds_read2_b32 v[44:45], v5 offset0:4 offset1:69
	ds_read2_b32 v[46:47], v5 offset0:134 offset1:199
	v_lshl_add_u64 v[18:19], v[18:19], 1, v[8:9]
	v_or_b32_e32 v5, v12, v29
	global_store_dwordx4 v[18:19], v[14:17], off
	v_mad_i64_i32 v[18:19], s[0:1], v6, v5, 0
	v_cndmask_b32_e32 v5, v31, v32, vcc
	v_lshl_add_u32 v5, v5, 2, v23
	s_waitcnt lgkmcnt(3)
	v_cvt_pk_bf16_f32 v14, v40, v41
	s_waitcnt lgkmcnt(2)
	v_cvt_pk_bf16_f32 v15, v42, v43
	ds_read2_b32 v[40:41], v5 offset1:65
	ds_read2_b32 v[42:43], v5 offset0:130 offset1:195
	v_add_u32_e32 v5, 0x400, v5
	s_waitcnt lgkmcnt(3)
	v_cvt_pk_bf16_f32 v16, v44, v45
	s_waitcnt lgkmcnt(2)
	v_cvt_pk_bf16_f32 v17, v46, v47
	ds_read2_b32 v[44:45], v5 offset0:4 offset1:69
	ds_read2_b32 v[46:47], v5 offset0:134 offset1:199
	v_lshl_add_u64 v[18:19], v[18:19], 1, v[8:9]
	v_or_b32_e32 v5, v12, v31
	global_store_dwordx4 v[18:19], v[14:17], off
	v_mad_i64_i32 v[18:19], s[0:1], v6, v5, 0
	v_cndmask_b32_e32 v5, v33, v34, vcc
	v_lshl_add_u32 v5, v5, 2, v23
	s_waitcnt lgkmcnt(3)
	v_cvt_pk_bf16_f32 v14, v40, v41
	s_waitcnt lgkmcnt(2)
	v_cvt_pk_bf16_f32 v15, v42, v43
	ds_read2_b32 v[40:41], v5 offset1:65
	ds_read2_b32 v[42:43], v5 offset0:130 offset1:195
	v_add_u32_e32 v5, 0x400, v5
	s_waitcnt lgkmcnt(3)
	v_cvt_pk_bf16_f32 v16, v44, v45
	s_waitcnt lgkmcnt(2)
	v_cvt_pk_bf16_f32 v17, v46, v47
	ds_read2_b32 v[44:45], v5 offset0:4 offset1:69
	ds_read2_b32 v[46:47], v5 offset0:134 offset1:199
	v_lshl_add_u64 v[18:19], v[18:19], 1, v[8:9]
	v_or_b32_e32 v5, v12, v33
	global_store_dwordx4 v[18:19], v[14:17], off
	v_mad_i64_i32 v[18:19], s[0:1], v6, v5, 0
	v_cndmask_b32_e32 v5, v35, v36, vcc
	v_lshl_add_u32 v5, v5, 2, v23
	s_waitcnt lgkmcnt(3)
	v_cvt_pk_bf16_f32 v14, v40, v41
	s_waitcnt lgkmcnt(2)
	v_cvt_pk_bf16_f32 v15, v42, v43
	ds_read2_b32 v[40:41], v5 offset1:65
	ds_read2_b32 v[42:43], v5 offset0:130 offset1:195
	v_add_u32_e32 v5, 0x400, v5
	s_waitcnt lgkmcnt(3)
	v_cvt_pk_bf16_f32 v16, v44, v45
	s_waitcnt lgkmcnt(2)
	v_cvt_pk_bf16_f32 v17, v46, v47
	ds_read2_b32 v[44:45], v5 offset0:4 offset1:69
	ds_read2_b32 v[46:47], v5 offset0:134 offset1:199
	v_lshl_add_u64 v[18:19], v[18:19], 1, v[8:9]
	v_or_b32_e32 v5, v12, v35
	global_store_dwordx4 v[18:19], v[14:17], off
	v_mad_i64_i32 v[18:19], s[0:1], v6, v5, 0
	v_cndmask_b32_e32 v5, v37, v38, vcc
	v_lshl_add_u32 v5, v5, 2, v23
	s_waitcnt lgkmcnt(3)
	v_cvt_pk_bf16_f32 v14, v40, v41
	s_waitcnt lgkmcnt(2)
	v_cvt_pk_bf16_f32 v15, v42, v43
	ds_read2_b32 v[40:41], v5 offset1:65
	ds_read2_b32 v[42:43], v5 offset0:130 offset1:195
	v_add_u32_e32 v5, 0x400, v5
	s_waitcnt lgkmcnt(3)
	v_cvt_pk_bf16_f32 v16, v44, v45
	s_waitcnt lgkmcnt(2)
	v_cvt_pk_bf16_f32 v17, v46, v47
	ds_read2_b32 v[44:45], v5 offset0:4 offset1:69
	ds_read2_b32 v[46:47], v5 offset0:134 offset1:199
	v_or_b32_e32 v5, v12, v37
	v_lshl_add_u64 v[18:19], v[18:19], 1, v[8:9]
	v_mad_i64_i32 v[6:7], s[0:1], v6, v5, 0
	global_store_dwordx4 v[18:19], v[14:17], off
	v_lshl_add_u64 v[6:7], v[6:7], 1, v[8:9]
	v_readlane_b32 s0, v254, 40
	s_waitcnt lgkmcnt(3)
	v_cvt_pk_bf16_f32 v14, v40, v41
	s_waitcnt lgkmcnt(2)
	v_cvt_pk_bf16_f32 v15, v42, v43
	s_waitcnt lgkmcnt(1)
	v_cvt_pk_bf16_f32 v16, v44, v45
	s_waitcnt lgkmcnt(0)
	v_cvt_pk_bf16_f32 v17, v46, v47
	global_store_dwordx4 v[6:7], v[14:17], off
	v_cmp_le_u32_e32 vcc, s99, v20
	v_mov_b32_e32 v5, 0x100000
	v_add_u32_e32 v20, s98, v20
	v_cndmask_b32_e32 v20, v20, v5, vcc
	s_movk_i32 s0, 0x11df
	s_waitcnt lgkmcnt(0)
	v_cmp_lt_i32_e32 vcc, s0, v20
	s_or_b64 s[6:7], vcc, s[6:7]
	v_readlane_b32 s1, v254, 41
	s_andn2_b64 exec, exec, s[6:7]
	s_cbranch_execz .LBB0_49
